# time-division of the staging waves' LDS write bursts: the upper two staging waves start their shared-buffer writes ~580 cycles after the lower two (on top of W)
# baseline (speedup 1.0000x reference)
.Lsc_gf_go1:
	ds_read_b32 v185, v183
	ds_read_b32 v186, v183 offset:256
	ds_read_b32 v187, v183 offset:512
	s_waitcnt lgkmcnt(0)
	v_and_b32_e32 v185, v174, v185
	v_and_b32_e32 v186, v175, v186
	v_and_b32_e32 v187, v176, v187
	v_add_f32_e32 v185, v185, v186
	v_add_f32_e32 v185, v185, v187
	v_fma_f32 v124, v124, s14, v185
	v_fma_f32 v125, v125, s14, v185
	v_fma_f32 v126, v126, s14, v185
	v_fma_f32 v127, v127, s14, v185
	v_fma_f32 v128, v128, s14, v185
	v_fma_f32 v129, v129, s14, v185
	v_fma_f32 v130, v130, s14, v185
	v_fma_f32 v131, v131, s14, v185
	v_exp_f32_e64 v188, -v185
	v_exp_f32_e64 v124, -v124
	v_exp_f32_e64 v125, -v125
	v_exp_f32_e64 v126, -v126
	v_exp_f32_e64 v127, -v127
	v_exp_f32_e64 v128, -v128
	v_exp_f32_e64 v129, -v129
	v_exp_f32_e64 v130, -v130
	v_exp_f32_e64 v131, -v131
	s_nop 0
	ds_write_b32 v155, v188
	ds_write_b32 v155, v124 offset:256
	ds_write_b32 v155, v125 offset:512
	ds_write_b32 v155, v126 offset:768
	ds_write_b32 v155, v127 offset:1024
	ds_write_b32 v155, v128 offset:1280
	ds_write_b32 v155, v129 offset:1536
	ds_write_b32 v155, v130 offset:1792
	ds_write_b32 v155, v131 offset:2048
	v_mov_b32_e32 v161, v131
	s_waitcnt lgkmcnt(0)
	ds_read_b128 v[64:67], v153 offset:2048
	ds_read_b128 v[68:71], v153 offset:2176
	ds_read_b128 v[116:119], v153 offset:2304
	ds_read_b128 v[120:123], v153 offset:2432
	s_waitcnt lgkmcnt(0)
	v_rcp_f32_e32 v124, v116
	v_rcp_f32_e32 v125, v117
	v_rcp_f32_e32 v126, v118
	v_rcp_f32_e32 v127, v119
	v_rcp_f32_e32 v128, v120
	v_rcp_f32_e32 v129, v121
	v_rcp_f32_e32 v130, v122
	v_rcp_f32_e32 v131, v123
	s_nop 1
	v_pk_mul_f32 v[72:73], v[72:73], v[124:125]
	v_pk_mul_f32 v[80:81], v[80:81], v[124:125]
	v_pk_mul_f32 v[88:89], v[88:89], v[64:65]
	v_pk_mul_f32 v[96:97], v[96:97], v[116:117]
	v_pk_mul_f32 v[74:75], v[74:75], v[126:127]
	v_pk_mul_f32 v[82:83], v[82:83], v[126:127]
	v_pk_mul_f32 v[90:91], v[90:91], v[66:67]
	v_pk_mul_f32 v[98:99], v[98:99], v[118:119]
	v_pk_mul_f32 v[76:77], v[76:77], v[128:129]
	v_pk_mul_f32 v[84:85], v[84:85], v[128:129]
	v_pk_mul_f32 v[92:93], v[92:93], v[68:69]
	v_pk_mul_f32 v[100:101], v[100:101], v[120:121]
	v_pk_mul_f32 v[78:79], v[78:79], v[130:131]
	v_pk_mul_f32 v[86:87], v[86:87], v[130:131]
	v_pk_mul_f32 v[94:95], v[94:95], v[70:71]
	v_pk_mul_f32 v[102:103], v[102:103], v[122:123]
	global_load_dwordx2 v[28:29], v5, s[36:37]
	global_load_dwordx2 v[30:31], v5, s[36:37] offset:64
	global_load_dwordx2 v[32:33], v5, s[38:39]
	global_load_dwordx2 v[34:35], v5, s[38:39] offset:64
	global_load_dwordx2 v[36:37], v5, s[40:41]
	global_load_dwordx2 v[38:39], v5, s[40:41] offset:64
	global_load_dwordx2 v[40:41], v5, s[42:43]
	global_load_dwordx2 v[42:43], v5, s[42:43] offset:64
	global_load_dword v44, v6, s[46:47]
	global_load_dword v45, v9, s[44:45]
	v_add_u32_e32 v5, s54, v5
	v_add_u32_e32 v6, s55, v6
	v_add_u32_e32 v9, s54, v9
	s_cmp_lt_u32 s7, 6
	s_cbranch_scc1 .Lsc_stg1
	s_sleep 9
.Lsc_stg1:
	ds_write_b32 v159, v161 offset:0
	ds_write_b128 v8, v[72:75] offset:0
	s_sleep 1
	ds_write_b128 v8, v[76:79] offset:128
	ds_write_b128 v8, v[80:83] offset:256
	s_sleep 1
	ds_write_b128 v8, v[84:87] offset:384
	ds_write2_b32 v138, v96, v97 offset0:1 offset1:3
	s_sleep 1
	ds_write2_b32 v139, v88, v89 offset0:0 offset1:2
	ds_write2_b32 v138, v98, v99 offset0:65 offset1:67
	s_sleep 1
	ds_write2_b32 v139, v90, v91 offset0:64 offset1:66
	ds_write2_b32 v138, v100, v101 offset0:33 offset1:35
	s_sleep 1
	ds_write2_b32 v139, v92, v93 offset0:32 offset1:34
	ds_write2_b32 v138, v102, v103 offset0:97 offset1:99
	s_sleep 1
	ds_write2_b32 v139, v94, v95 offset0:96 offset1:98
	ds_write2_b32 v142, v104, v105 offset1:36
	s_sleep 1
	s_cmp_lg_u32 s7, 4
	s_cbranch_scc1 .Lsc_nokb2
	s_and_saveexec_b64 s[68:69], s[12:13]
	ds_write_b128 v158, v[88:91] offset:0
	ds_write_b128 v158, v[92:95] offset:128
	s_mov_b64 exec, s[68:69]
.Lsc_nokb2:
	s_add_i32 s6, s6, 1
	v_add_u32_e32 v146, 1, v146
	s_waitcnt lgkmcnt(0)
	ds_write_b32 v145, v146
	s_waitcnt vmcnt(10)
	v_lshlrev_b32_e32 v64, 16, v54
	v_and_b32_e32 v65, 0xffff0000, v54
	v_lshlrev_b32_e32 v66, 16, v55
	v_and_b32_e32 v67, 0xffff0000, v55
	v_lshlrev_b32_e32 v68, 16, v56
	v_and_b32_e32 v69, 0xffff0000, v56
	v_lshlrev_b32_e32 v70, 16, v57
	v_and_b32_e32 v71, 0xffff0000, v57
	ds_write_b128 v153, v[64:67]
	ds_write_b128 v153, v[68:71] offset:128
	s_waitcnt lgkmcnt(0)
	ds_read_b32 v124, v154 offset:0
	ds_read_b32 v125, v154 offset:256
	ds_read_b32 v126, v154 offset:512
	ds_read_b32 v127, v154 offset:768
	ds_read_b32 v128, v154 offset:1024
	ds_read_b32 v129, v154 offset:1280
	ds_read_b32 v130, v154 offset:1536
	ds_read_b32 v131, v154 offset:1792
	v_lshlrev_b32_e32 v108, 16, v50
	v_and_b32_e32 v109, 0xffff0000, v50
	v_lshlrev_b32_e32 v110, 16, v58
	v_and_b32_e32 v111, 0xffff0000, v58
	v_lshlrev_b32_e32 v96, 16, v46
	v_and_b32_e32 v97, 0xffff0000, v46
	v_pk_mul_f32 v[114:115], v[12:13], v[108:109]
	v_pk_fma_f32 v[112:113], v[20:21], v[110:111], v[190:191]
	v_pk_mul_f32 v[88:89], v[62:63], v[114:115] op_sel_hi:[0,1]
	v_pk_mul_f32 v[72:73], v[112:113], v[108:109]
	v_pk_mul_f32 v[80:81], v[88:89], v[110:111]
	v_lshlrev_b32_e32 v108, 16, v51
	v_and_b32_e32 v109, 0xffff0000, v51
	v_lshlrev_b32_e32 v110, 16, v59
	v_and_b32_e32 v111, 0xffff0000, v59
	v_lshlrev_b32_e32 v98, 16, v47
	v_and_b32_e32 v99, 0xffff0000, v47
	v_pk_mul_f32 v[114:115], v[14:15], v[108:109]
	v_pk_fma_f32 v[112:113], v[22:23], v[110:111], v[192:193]
	v_pk_mul_f32 v[90:91], v[62:63], v[114:115] op_sel_hi:[0,1]
	v_pk_mul_f32 v[74:75], v[112:113], v[108:109]
	v_pk_mul_f32 v[82:83], v[90:91], v[110:111]
	v_lshlrev_b32_e32 v108, 16, v52
	v_and_b32_e32 v109, 0xffff0000, v52
	v_lshlrev_b32_e32 v110, 16, v60
	v_and_b32_e32 v111, 0xffff0000, v60
	v_lshlrev_b32_e32 v100, 16, v48
	v_and_b32_e32 v101, 0xffff0000, v48
	v_pk_mul_f32 v[114:115], v[16:17], v[108:109]
	v_pk_fma_f32 v[112:113], v[24:25], v[110:111], v[194:195]
	v_pk_mul_f32 v[92:93], v[62:63], v[114:115] op_sel_hi:[0,1]
	v_pk_mul_f32 v[76:77], v[112:113], v[108:109]
	v_pk_mul_f32 v[84:85], v[92:93], v[110:111]
	v_lshlrev_b32_e32 v108, 16, v53
	v_and_b32_e32 v109, 0xffff0000, v53
	v_lshlrev_b32_e32 v110, 16, v61
	v_and_b32_e32 v111, 0xffff0000, v61
	v_lshlrev_b32_e32 v102, 16, v49
	v_and_b32_e32 v103, 0xffff0000, v49
	v_pk_mul_f32 v[114:115], v[18:19], v[108:109]
	v_pk_fma_f32 v[112:113], v[26:27], v[110:111], v[196:197]
	v_pk_mul_f32 v[94:95], v[62:63], v[114:115] op_sel_hi:[0,1]
	v_pk_mul_f32 v[78:79], v[112:113], v[108:109]
	v_pk_mul_f32 v[86:87], v[94:95], v[110:111]
	v_lshlrev_b32_e32 v104, 16, v63
	v_and_b32_e32 v105, 0xffff0000, v63
	s_waitcnt lgkmcnt(0)
	v_add_f32_e32 v125, v124, v125
	v_add_f32_e32 v126, v125, v126
	v_add_f32_e32 v127, v126, v127
	v_add_f32_e32 v128, v127, v128
	v_add_f32_e32 v129, v128, v129
	v_add_f32_e32 v130, v129, v130
	v_add_f32_e32 v131, v130, v131
	s_and_b32 s72, s6, 3
	s_lshl_b32 s72, s72, 10
	v_add_u32_e32 v182, s72, v180
	v_add_u32_e32 v183, s72, v181
	v_mul_f32_e32 v189, 0x3fb8aa3b, v131
	ds_write_b32 v182, v189
	v_add_u32_e32 v184, 1, v146
	s_waitcnt lgkmcnt(0)
	ds_write_b32 v162, v184
	s_add_u32 s73, s6, 1
	s_mov_b32 s69, 0x100000

.Lsc_gf_go2:
	ds_read_b32 v185, v183
	ds_read_b32 v186, v183 offset:256
	ds_read_b32 v187, v183 offset:512
	s_waitcnt lgkmcnt(0)
	v_and_b32_e32 v185, v174, v185
	v_and_b32_e32 v186, v175, v186
	v_and_b32_e32 v187, v176, v187
	v_add_f32_e32 v185, v185, v186
	v_add_f32_e32 v185, v185, v187
	v_fma_f32 v124, v124, s14, v185
	v_fma_f32 v125, v125, s14, v185
	v_fma_f32 v126, v126, s14, v185
	v_fma_f32 v127, v127, s14, v185
	v_fma_f32 v128, v128, s14, v185
	v_fma_f32 v129, v129, s14, v185
	v_fma_f32 v130, v130, s14, v185
	v_fma_f32 v131, v131, s14, v185
	v_exp_f32_e64 v188, -v185
	v_exp_f32_e64 v124, -v124
	v_exp_f32_e64 v125, -v125
	v_exp_f32_e64 v126, -v126
	v_exp_f32_e64 v127, -v127
	v_exp_f32_e64 v128, -v128
	v_exp_f32_e64 v129, -v129
	v_exp_f32_e64 v130, -v130
	v_exp_f32_e64 v131, -v131
	s_nop 0
	ds_write_b32 v155, v188
	ds_write_b32 v155, v124 offset:256
	ds_write_b32 v155, v125 offset:512
	ds_write_b32 v155, v126 offset:768
	ds_write_b32 v155, v127 offset:1024
	ds_write_b32 v155, v128 offset:1280
	ds_write_b32 v155, v129 offset:1536
	ds_write_b32 v155, v130 offset:1792
	ds_write_b32 v155, v131 offset:2048
	v_mov_b32_e32 v161, v131
	s_waitcnt lgkmcnt(0)
	ds_read_b128 v[64:67], v153 offset:2048
	ds_read_b128 v[68:71], v153 offset:2176
	ds_read_b128 v[116:119], v153 offset:2304
	ds_read_b128 v[120:123], v153 offset:2432
	s_waitcnt lgkmcnt(0)
	v_rcp_f32_e32 v124, v116
	v_rcp_f32_e32 v125, v117
	v_rcp_f32_e32 v126, v118
	v_rcp_f32_e32 v127, v119
	v_rcp_f32_e32 v128, v120
	v_rcp_f32_e32 v129, v121
	v_rcp_f32_e32 v130, v122
	v_rcp_f32_e32 v131, v123
	s_nop 1
	v_pk_mul_f32 v[72:73], v[72:73], v[124:125]
	v_pk_mul_f32 v[80:81], v[80:81], v[124:125]
	v_pk_mul_f32 v[88:89], v[88:89], v[64:65]
	v_pk_mul_f32 v[96:97], v[96:97], v[116:117]
	v_pk_mul_f32 v[74:75], v[74:75], v[126:127]
	v_pk_mul_f32 v[82:83], v[82:83], v[126:127]
	v_pk_mul_f32 v[90:91], v[90:91], v[66:67]
	v_pk_mul_f32 v[98:99], v[98:99], v[118:119]
	v_pk_mul_f32 v[76:77], v[76:77], v[128:129]
	v_pk_mul_f32 v[84:85], v[84:85], v[128:129]
	v_pk_mul_f32 v[92:93], v[92:93], v[68:69]
	v_pk_mul_f32 v[100:101], v[100:101], v[120:121]
	v_pk_mul_f32 v[78:79], v[78:79], v[130:131]
	v_pk_mul_f32 v[86:87], v[86:87], v[130:131]
	v_pk_mul_f32 v[94:95], v[94:95], v[70:71]
	v_pk_mul_f32 v[102:103], v[102:103], v[122:123]
	global_load_dwordx2 v[46:47], v5, s[36:37]
	global_load_dwordx2 v[48:49], v5, s[36:37] offset:64
	global_load_dwordx2 v[50:51], v5, s[38:39]
	global_load_dwordx2 v[52:53], v5, s[38:39] offset:64
	global_load_dwordx2 v[54:55], v5, s[40:41]
	global_load_dwordx2 v[56:57], v5, s[40:41] offset:64
	global_load_dwordx2 v[58:59], v5, s[42:43]
	global_load_dwordx2 v[60:61], v5, s[42:43] offset:64
	global_load_dword v62, v6, s[46:47]
	global_load_dword v63, v9, s[44:45]
	v_add_u32_e32 v5, s54, v5
	v_add_u32_e32 v6, s55, v6
	v_add_u32_e32 v9, s54, v9
	s_cmp_lt_u32 s7, 6
	s_cbranch_scc1 .Lsc_stg3
	s_sleep 9
.Lsc_stg3:
	ds_write_b32 v159, v161 offset:34816
	ds_write_b128 v8, v[72:75] offset:34816
	s_sleep 1
	ds_write_b128 v8, v[76:79] offset:34944
	ds_write_b128 v8, v[80:83] offset:35072
	s_sleep 1
	ds_write_b128 v8, v[84:87] offset:35200
	ds_write2_b32 v140, v96, v97 offset0:1 offset1:3
	s_sleep 1
	ds_write2_b32 v141, v88, v89 offset0:0 offset1:2
	ds_write2_b32 v140, v98, v99 offset0:65 offset1:67
	s_sleep 1
	ds_write2_b32 v141, v90, v91 offset0:64 offset1:66
	ds_write2_b32 v140, v100, v101 offset0:33 offset1:35
	s_sleep 1
	ds_write2_b32 v141, v92, v93 offset0:32 offset1:34
	ds_write2_b32 v140, v102, v103 offset0:97 offset1:99
	s_sleep 1
	ds_write2_b32 v141, v94, v95 offset0:96 offset1:98
	ds_write2_b32 v143, v104, v105 offset1:36
	s_sleep 1
	s_cmp_lg_u32 s7, 4
	s_cbranch_scc1 .Lsc_nokb4
	s_and_saveexec_b64 s[68:69], s[12:13]
	ds_write_b128 v158, v[88:91] offset:34816
	ds_write_b128 v158, v[92:95] offset:34944
	s_mov_b64 exec, s[68:69]
.Lsc_nokb4:
	s_add_i32 s6, s6, 1
	v_add_u32_e32 v146, 1, v146
	s_waitcnt lgkmcnt(0)
	ds_write_b32 v145, v146

.Lsc_G_gom0:
	s_cmp_lt_u32 s7, 6
	s_cbranch_scc1 .Lsc_stg5
	s_sleep 9
